# attention row-max: 56-op canonicalize+max tree replaced by 16 v_max3 directly on MFMA outputs (3 tile-loop bodies) on top of v023
# speedup vs baseline: 1.0093x; 1.0075x over previous
; #define LAS __attribute__((address_space(3)))
; DI float fast_exp2(float x) { return __builtin_amdgcn_exp2f(x); }
; #define MFMA16(a, b, c) __builtin_amdgcn_mfma_f32_16x16x32_bf16((a), (b), (c), 0, 0, 0)
; DI void at_qk(f32x4 (&s1)[4], f32x4 (&s2)[4], const LAS unsigned char* buf, const bf16x8 q1, const bf16x8 q2, const f32x4 (&ci)[4], int hh, int fr, int fq) {
; #pragma unroll
;     for (int k4 = 0; k4 < 4; ++k4) { const LAS unsigned char* kr = buf + AT_K + (16 * k4 + fr) * 272 + hh * 128 + fq * 16;
;         s1[k4] = MFMA16(ld8l(kr), q1, ci[k4]); s2[k4] = MFMA16(ld8l(kr + 64), q2, ci[k4]); }
; }
; DI void at_exp(f32x4 (&s1)[4], f32x4 (&s2)[4], float& ps1, float& ps2) {
;     f32x4 a1 = (f32x4){0.f, 0.f, 0.f, 0.f}, a2 = a1;
; #pragma unroll
;     for (int k4 = 0; k4 < 4; ++k4) {
; #pragma unroll
;         for (int j = 0; j < 4; ++j) { s1[k4][j] = fast_exp2(s1[k4][j]); s2[k4][j] = fast_exp2(s2[k4][j]); }
;         a1 = a1 + s1[k4]; a2 = a2 + s2[k4]; }
;     ps1 = (a1[0] + a1[1]) + (a1[2] + a1[3]); ps2 = (a2[0] + a2[1]) + (a2[2] + a2[3]);
; }
; template <int VAR>
; DI void attn_tile(AtState& S, const LAS unsigned char* buf, const bf16x8 q1, const bf16x8 q2, int kt, bool diag, int qpos0, int qpos_l, float slope2, float adv, float decay, int hh, int fr, int fq) {
;     ...
;     } else {
;         asm volatile("; attention: fast tile" ::: "memory");
;         at_qk(s1, s2, buf, q1, q2, S.cinit, hh, fr, fq);
;         S.ref += adv;
;         at_exp(s1, s2, ps1, ps2);
;         if (__any(!(ps1 + ps2 < 0x1p60f))) {
;             asm volatile("; attention: bump" ::: "memory");
;             at_qk(s1, s2, buf, q1, q2, S.cinit, hh, fr, fq);
;             float lm = -1e30f;
; #pragma unroll
;             for (int k4 = 0; k4 < 4; ++k4)
; #pragma unroll
;                 for (int j = 0; j < 4; ++j) lm = fmaxf(lm, fmaxf(s1[k4][j], s2[k4][j]));
;             lm = fmaxf(lm, __shfl_xor(lm, 16)); lm = fmaxf(lm, __shfl_xor(lm, 32));
.LBB0_1376:
	s_add_i32 s27, s26, -1
	s_min_i32 s14, s27, s25
	s_ashr_i32 s15, s14, 31
	s_add_i32 s28, s22, s26
	s_lshl_b64 s[14:15], s[14:15], 18
	s_add_u32 s14, s0, s14
	s_addc_u32 s15, s1, s15
	global_load_dwordx4 v[28:31], v144, s[14:15] offset:1024
	global_load_dwordx4 v[32:35], v144, s[14:15] offset:1536
	global_load_dwordx4 v[36:39], v146, s[14:15] offset:1024
	global_load_dwordx4 v[40:43], v146, s[14:15] offset:1536
	s_cmpk_eq_i32 s28, 0x42
	s_cselect_b64 s[16:17], -1, 0
	s_cmp_eq_u32 s26, 3
	s_cselect_b64 s[14:15], -1, 0
	s_or_b64 s[18:19], s[14:15], s[16:17]
	s_andn2_b64 vcc, exec, s[18:19]
	s_mov_b64 s[18:19], -1
	s_cbranch_vccz .LBB0_1381
	ds_read_b128 v[76:79], v213
	ds_read_b128 v[80:83], v213 offset:64
	ds_read_b128 v[96:99], v213 offset:4352
	ds_read_b128 v[104:107], v213 offset:4416
	ds_read_b128 v[108:111], v213 offset:8704
	ds_read_b128 v[112:115], v213 offset:8768
	ds_read_b128 v[116:119], v213 offset:13056
	ds_read_b128 v[120:123], v213 offset:13120
	s_waitcnt lgkmcnt(7)
	v_mfma_f32_16x16x32_bf16 v[76:79], v[76:79], v[4:7], v[44:47]
	v_add_f32_e32 v215, v205, v214
	s_waitcnt lgkmcnt(6)
	v_mfma_f32_16x16x32_bf16 v[80:83], v[80:83], v[8:11], v[44:47]
	s_waitcnt lgkmcnt(5)
	v_mfma_f32_16x16x32_bf16 v[96:99], v[96:99], v[4:7], v[48:51]
	s_nop 2
	v_exp_f32_e32 v164, v76
	v_exp_f32_e32 v165, v77
	v_exp_f32_e32 v168, v78
	s_waitcnt lgkmcnt(4)
	v_mfma_f32_16x16x32_bf16 v[104:107], v[104:107], v[8:11], v[48:51]
	v_exp_f32_e32 v169, v79
	v_exp_f32_e32 v162, v80
	v_exp_f32_e32 v163, v81
	s_waitcnt lgkmcnt(3)
	v_mfma_f32_16x16x32_bf16 v[108:111], v[108:111], v[4:7], v[52:55]
	v_exp_f32_e32 v166, v82
	v_exp_f32_e32 v167, v83
	v_exp_f32_e32 v172, v96
	s_waitcnt lgkmcnt(2)
	v_mfma_f32_16x16x32_bf16 v[76:79], v[112:115], v[8:11], v[52:55]
	v_exp_f32_e32 v170, v104
	v_exp_f32_e32 v173, v97
	v_exp_f32_e32 v176, v98
	s_waitcnt lgkmcnt(1)
	v_mfma_f32_16x16x32_bf16 v[80:83], v[116:119], v[4:7], v[56:59]
	v_exp_f32_e32 v177, v99
	v_exp_f32_e32 v174, v106
	v_exp_f32_e32 v175, v107
	s_waitcnt lgkmcnt(0)
	v_mfma_f32_16x16x32_bf16 v[112:115], v[120:123], v[8:11], v[56:59]
	v_exp_f32_e32 v171, v105
	v_exp_f32_e32 v180, v108
	v_exp_f32_e32 v178, v76
	v_exp_f32_e32 v181, v109
	v_exp_f32_e32 v179, v77
	v_exp_f32_e32 v184, v110
	v_exp_f32_e32 v185, v111
	v_exp_f32_e32 v182, v78
	v_exp_f32_e32 v183, v79
	v_exp_f32_e32 v188, v80
	v_exp_f32_e32 v186, v112
	v_exp_f32_e32 v189, v81
	v_exp_f32_e32 v192, v82
	v_exp_f32_e32 v193, v83
	v_exp_f32_e32 v190, v114
	v_exp_f32_e32 v191, v115
	v_exp_f32_e32 v187, v113
	v_pk_add_f32 v[124:125], v[164:165], 0 op_sel_hi:[1,0]
	v_pk_add_f32 v[126:127], v[168:169], 0 op_sel_hi:[1,0]
	v_pk_add_f32 v[116:117], v[162:163], 0 op_sel_hi:[1,0]
	v_pk_add_f32 v[118:119], v[166:167], 0 op_sel_hi:[1,0]
	v_pk_add_f32 v[96:97], v[126:127], v[176:177]
	v_pk_add_f32 v[98:99], v[124:125], v[172:173]
	v_pk_add_f32 v[104:105], v[118:119], v[174:175]
	v_pk_add_f32 v[106:107], v[116:117], v[170:171]
	v_pk_add_f32 v[76:77], v[98:99], v[180:181]
	v_pk_add_f32 v[78:79], v[96:97], v[184:185]
	v_pk_add_f32 v[96:97], v[106:107], v[178:179]
	v_pk_add_f32 v[98:99], v[104:105], v[182:183]
	v_pk_add_f32 v[78:79], v[78:79], v[192:193]
	v_pk_add_f32 v[76:77], v[76:77], v[188:189]
	v_pk_add_f32 v[80:81], v[98:99], v[190:191]
	v_pk_add_f32 v[82:83], v[96:97], v[186:187]
	v_mov_b32_e32 v97, v76
	v_mov_b32_e32 v96, v82
	v_mov_b32_e32 v76, v83
	v_mov_b32_e32 v82, v80
	v_mov_b32_e32 v83, v78
	v_mov_b32_e32 v78, v81
	v_pk_add_f32 v[76:77], v[96:97], v[76:77]
	v_pk_add_f32 v[78:79], v[82:83], v[78:79]
	s_nop 0
	v_pk_add_f32 v[194:195], v[76:77], v[78:79]
	s_nop 0
	v_add_f32_e32 v3, v195, v194
	v_cmp_ngt_f32_e32 vcc, s65, v3
	s_cbranch_vccz .LBB0_1394
	ds_read_b128 v[76:79], v213
	ds_read_b128 v[80:83], v213 offset:64
	ds_read_b128 v[96:99], v213 offset:4352
	ds_read_b128 v[104:107], v213 offset:4416
	ds_read_b128 v[108:111], v213 offset:8704
	ds_read_b128 v[112:115], v213 offset:8768
	ds_read_b128 v[116:119], v213 offset:13056
	ds_read_b128 v[120:123], v213 offset:13120
	s_waitcnt lgkmcnt(7)
	v_mfma_f32_16x16x32_bf16 v[76:79], v[76:79], v[4:7], v[44:47]
	s_waitcnt lgkmcnt(6)
	v_mfma_f32_16x16x32_bf16 v[80:83], v[80:83], v[8:11], v[44:47]
	s_waitcnt lgkmcnt(5)
	v_mfma_f32_16x16x32_bf16 v[96:99], v[96:99], v[4:7], v[48:51]
	s_waitcnt lgkmcnt(4)
	v_mfma_f32_16x16x32_bf16 v[104:107], v[104:107], v[8:11], v[48:51]
	s_waitcnt lgkmcnt(3)
	v_mfma_f32_16x16x32_bf16 v[108:111], v[108:111], v[4:7], v[52:55]
	s_waitcnt lgkmcnt(2)
	v_mfma_f32_16x16x32_bf16 v[112:115], v[112:115], v[8:11], v[52:55]
	s_waitcnt lgkmcnt(1)
	v_mfma_f32_16x16x32_bf16 v[116:119], v[116:119], v[4:7], v[56:59]
	s_waitcnt lgkmcnt(0)
	v_mfma_f32_16x16x32_bf16 v[120:123], v[120:123], v[8:11], v[56:59]
	v_max3_f32 v3, v76, v80, s60
	v_max3_f32 v3, v3, v77, v81
	v_max3_f32 v3, v3, v78, v82
	v_max3_f32 v3, v3, v79, v83
	v_max3_f32 v3, v3, v96, v104
	v_max3_f32 v3, v3, v97, v105
	v_max3_f32 v3, v3, v98, v106
	v_max3_f32 v3, v3, v99, v107
	v_max3_f32 v3, v3, v108, v112
	v_max3_f32 v3, v3, v109, v113
	v_max3_f32 v3, v3, v110, v114
	v_max3_f32 v3, v3, v111, v115
	v_max3_f32 v3, v3, v116, v120
	v_max3_f32 v3, v3, v117, v121
	v_max3_f32 v3, v3, v118, v122
	v_max3_f32 v3, v3, v119, v123
	v_and_b32_e32 v125, 64, v198
	v_mov_b32_e32 v124, v3
	v_mov_b32_e32 v255, v3
	s_nop 1
	v_permlane16_swap_b32_e32 v124, v255
	s_waitcnt lgkmcnt(0)
	v_max_f32_e32 v3, v124, v255
	v_mov_b32_e32 v124, v3
	v_mov_b32_e32 v255, v3
	s_nop 1
	v_permlane32_swap_b32_e32 v124, v255
	s_waitcnt lgkmcnt(0)
; #define LAS __attribute__((address_space(3)))
; DI float fast_exp2(float x) { return __builtin_amdgcn_exp2f(x); }
; #define MFMA16(a, b, c) __builtin_amdgcn_mfma_f32_16x16x32_bf16((a), (b), (c), 0, 0, 0)
; DI bf16x8 packp(f32x4 a, f32x4 b) { return __builtin_bit_cast(bf16x8, pack8(a, b)); }
; DI void at_pv(AtState& S, const f32x4 (&s1)[4], const f32x4 (&s2)[4], float alpha, float ps1, float ps2, const LAS unsigned char* buf, int hh, int fq, int tq, int tp) {
;     S.l1 = S.l1 * alpha + ps1; S.l2 = S.l2 * alpha + ps2;
; #pragma unroll
;     for (int dt = 0; dt < 4; ++dt) { S.O1[dt] = S.O1[dt] * alpha; S.O2[dt] = S.O2[dt] * alpha; }
;     bf16x8 p1[2], p2[2];
; #pragma unroll
;     for (int s = 0; s < 2; ++s) { p1[s] = packp(s1[2 * s], s1[2 * s + 1]); p2[s] = packp(s2[2 * s], s2[2 * s + 1]); }
; #pragma unroll
;     for (int dh = 0; dh < 2; ++dh) {
;         bf16x8 vt[2][2];
; #pragma unroll
;         for (int d2 = 0; d2 < 2; ++d2)
; #pragma unroll
;             for (int s = 0; s < 2; ++s) { const int dt = 2 * dh + d2; const LAS unsigned char* vr = buf + AT_V + (32 * s + 4 * fq + tq) * 288 + (hh * 64 + 16 * dt + 4 * tp) * 2; vt[d2][s] = cat44(tr4(vr), tr4(vr + 16 * 288)); }
;         __builtin_amdgcn_s_setprio(1);
; #pragma unroll
;         for (int s = 0; s < 2; ++s)
; #pragma unroll
;             for (int d2 = 0; d2 < 2; ++d2) { const int dt = 2 * dh + d2; S.O1[dt] = MFMA16(vt[d2][s], p1[s], S.O1[dt]); S.O2[dt] = MFMA16(vt[d2][s], p2[s], S.O2[dt]); }
; template <int VAR>
; DI void attn_tile(AtState& S, const LAS unsigned char* buf, const bf16x8 q1, const bf16x8 q2, int kt, bool diag, int qpos0, int qpos_l, float slope2, float adv, float decay, int hh, int fr, int fq) {
;     ...
;             float lm = -1e30f;
; #pragma unroll
;             for (int k4 = 0; k4 < 4; ++k4)
; #pragma unroll
;                 for (int j = 0; j < 4; ++j) lm = fmaxf(lm, fmaxf(s1[k4][j], s2[k4][j]));
;             lm = fmaxf(lm, __shfl_xor(lm, 16)); lm = fmaxf(lm, __shfl_xor(lm, 32));
;             const float bump = fmaxf(lm, 0.f);
;             const float alpha = decay * fast_exp2(-bump); S.ref += bump;
; #pragma unroll
;             for (int k4 = 0; k4 < 4; ++k4) { s1[k4] = s1[k4] - bump; s2[k4] = s2[k4] - bump; S.cinit[k4] = S.cinit[k4] - bump; }
;             at_exp(s1, s2, ps1, ps2);
;             at_pv(S, s1, s2, alpha, ps1, ps2, buf, hh, fq, tq, tp);
	v_max3_f32 v124, v255, v124, 0
	v_sub_f32_e32 v126, v79, v124
	v_sub_f32_e32 v127, v78, v124
	v_sub_f32_e32 v128, v77, v124
	v_sub_f32_e32 v129, v76, v124
	v_sub_f32_e32 v130, v83, v124
	v_sub_f32_e32 v131, v82, v124
	v_sub_f32_e32 v132, v81, v124
	v_sub_f32_e32 v133, v80, v124
	v_sub_f32_e32 v134, v99, v124
	v_sub_f32_e32 v135, v98, v124
	v_sub_f32_e32 v137, v97, v124
	v_sub_f32_e32 v138, v96, v124
	v_sub_f32_e32 v139, v107, v124
	v_sub_f32_e32 v151, v106, v124
	v_sub_f32_e32 v158, v105, v124
	v_sub_f32_e32 v159, v104, v124
	v_exp_f32_e32 v216, v129
	v_exp_f32_e32 v220, v133
	v_exp_f32_e32 v217, v128
	v_exp_f32_e32 v221, v132
	v_exp_f32_e32 v218, v127
	v_exp_f32_e32 v222, v131
	v_exp_f32_e32 v219, v126
	v_exp_f32_e32 v223, v130
	v_sub_f32_e32 v237, v111, v124
	v_sub_f32_e32 v236, v110, v124
	v_sub_f32_e32 v233, v109, v124
	v_sub_f32_e32 v232, v108, v124
	v_sub_f32_e32 v239, v115, v124
	v_sub_f32_e32 v238, v114, v124
	v_sub_f32_e32 v235, v113, v124
	v_sub_f32_e32 v234, v112, v124
	v_exp_f32_e32 v224, v138
	v_exp_f32_e32 v226, v159
	v_exp_f32_e32 v225, v137
	v_exp_f32_e32 v227, v158
	v_exp_f32_e32 v228, v135
	v_exp_f32_e32 v230, v151
	v_exp_f32_e32 v229, v134
	v_exp_f32_e32 v231, v139
	v_sub_f32_e32 v119, v119, v124
	v_sub_f32_e32 v118, v118, v124
	v_sub_f32_e32 v117, v117, v124
	v_sub_f32_e32 v116, v116, v124
	v_sub_f32_e32 v123, v123, v124
	v_sub_f32_e32 v122, v122, v124
	v_sub_f32_e32 v121, v121, v124
	v_sub_f32_e32 v120, v120, v124
	v_exp_f32_e32 v232, v232
	v_exp_f32_e32 v234, v234
	v_exp_f32_e32 v233, v233
	v_exp_f32_e32 v235, v235
	v_exp_f32_e32 v236, v236
	v_exp_f32_e32 v238, v238
	v_exp_f32_e32 v237, v237
	v_exp_f32_e32 v239, v239
	v_exp_f32_e32 v240, v116
	v_exp_f32_e32 v242, v120
	v_exp_f32_e32 v241, v117
	v_exp_f32_e32 v243, v121
	v_exp_f32_e32 v244, v118
	v_exp_f32_e32 v246, v122
	v_exp_f32_e32 v245, v119
	v_exp_f32_e32 v247, v123
	v_pk_add_f32 v[108:109], v[216:217], 0 op_sel_hi:[1,0]
	v_pk_add_f32 v[110:111], v[218:219], 0 op_sel_hi:[1,0]
	v_pk_add_f32 v[112:113], v[220:221], 0 op_sel_hi:[1,0]
	v_pk_add_f32 v[114:115], v[222:223], 0 op_sel_hi:[1,0]
	v_pk_add_f32 v[110:111], v[228:229], v[110:111]
	v_pk_add_f32 v[108:109], v[224:225], v[108:109]
	v_pk_add_f32 v[114:115], v[230:231], v[114:115]
	v_pk_add_f32 v[112:113], v[226:227], v[112:113]
	v_pk_add_f32 v[108:109], v[232:233], v[108:109]
	v_pk_add_f32 v[110:111], v[236:237], v[110:111]
	v_pk_add_f32 v[112:113], v[234:235], v[112:113]
	v_pk_add_f32 v[114:115], v[238:239], v[114:115]
	v_pk_add_f32 v[110:111], v[244:245], v[110:111]
	v_pk_add_f32 v[108:109], v[240:241], v[108:109]
	v_pk_add_f32 v[114:115], v[246:247], v[114:115]
	v_pk_add_f32 v[112:113], v[242:243], v[112:113]
	v_cvt_pk_bf16_f32 v216, v216, v217
	v_cvt_pk_bf16_f32 v217, v218, v219
	v_cvt_pk_bf16_f32 v218, v224, v225
	v_cvt_pk_bf16_f32 v219, v228, v229
	v_cvt_pk_bf16_f32 v220, v220, v221
	v_cvt_pk_bf16_f32 v221, v222, v223
	v_cvt_pk_bf16_f32 v222, v226, v227
	v_cvt_pk_bf16_f32 v223, v230, v231
	v_cvt_pk_bf16_f32 v224, v232, v233
	v_cvt_pk_bf16_f32 v225, v236, v237
	v_cvt_pk_bf16_f32 v226, v240, v241
	v_cvt_pk_bf16_f32 v227, v244, v245
	v_cvt_pk_bf16_f32 v228, v234, v235
	v_cvt_pk_bf16_f32 v229, v238, v239
	v_cvt_pk_bf16_f32 v230, v242, v243
	v_cvt_pk_bf16_f32 v231, v246, v247
	ds_read_b64_tr_b16 v[232:233], v208 offset:17408
	ds_read_b64_tr_b16 v[236:237], v208 offset:17440
	ds_read_b64_tr_b16 v[234:235], v208 offset:22016
	ds_read_b64_tr_b16 v[240:241], v208 offset:26624
	ds_read_b64_tr_b16 v[242:243], v208 offset:31232
	ds_read_b64_tr_b16 v[238:239], v208 offset:22048
	ds_read_b64_tr_b16 v[244:245], v208 offset:26656
	ds_read_b64_tr_b16 v[246:247], v208 offset:31264
	v_exp_f32_e64 v125, -v124
	v_mov_b32_e32 v116, v112
	v_mov_b32_e32 v117, v108
	v_mov_b32_e32 v108, v113
	v_mov_b32_e32 v112, v114
	v_mov_b32_e32 v113, v110
	v_mov_b32_e32 v110, v115
	v_pk_add_f32 v[108:109], v[116:117], v[108:109]
	v_pk_add_f32 v[110:111], v[112:113], v[110:111]
	v_mul_f32_e32 v136, v150, v125
	v_pk_add_f32 v[108:109], v[108:109], v[110:111]
	v_add_f32_e32 v3, v215, v124
	v_sub_f32_e32 v79, v47, v124
	v_sub_f32_e32 v78, v46, v124
	v_sub_f32_e32 v77, v45, v124
	v_sub_f32_e32 v76, v44, v124
	v_sub_f32_e32 v99, v51, v124
	v_sub_f32_e32 v98, v50, v124
	v_sub_f32_e32 v97, v49, v124
	v_sub_f32_e32 v96, v48, v124
	v_sub_f32_e32 v107, v55, v124
	v_sub_f32_e32 v106, v54, v124
	v_sub_f32_e32 v105, v53, v124
	v_sub_f32_e32 v104, v52, v124
	v_sub_f32_e32 v83, v59, v124
	v_sub_f32_e32 v82, v58, v124
	v_sub_f32_e32 v81, v57, v124
	v_sub_f32_e32 v80, v56, v124
	v_pk_fma_f32 v[158:159], v[156:157], v[136:137], v[108:109] op_sel_hi:[1,0,1]
	v_pk_mul_f32 v[110:111], v[66:67], v[136:137] op_sel_hi:[1,0]
	v_pk_mul_f32 v[108:109], v[64:65], v[136:137] op_sel_hi:[1,0]
	v_pk_mul_f32 v[114:115], v[74:75], v[136:137] op_sel_hi:[1,0]
	v_pk_mul_f32 v[112:113], v[72:73], v[136:137] op_sel_hi:[1,0]
	v_pk_mul_f32 v[118:119], v[62:63], v[136:137] op_sel_hi:[1,0]
	v_pk_mul_f32 v[116:117], v[60:61], v[136:137] op_sel_hi:[1,0]
	v_pk_mul_f32 v[122:123], v[70:71], v[136:137] op_sel_hi:[1,0]
	v_pk_mul_f32 v[120:121], v[68:69], v[136:137] op_sel_hi:[1,0]
	v_pk_mul_f32 v[126:127], v[90:91], v[136:137] op_sel_hi:[1,0]
	v_pk_mul_f32 v[124:125], v[88:89], v[136:137] op_sel_hi:[1,0]
	v_pk_mul_f32 v[130:131], v[102:103], v[136:137] op_sel_hi:[1,0]
	v_pk_mul_f32 v[128:129], v[100:101], v[136:137] op_sel_hi:[1,0]
	v_pk_mul_f32 v[134:135], v[86:87], v[136:137] op_sel_hi:[1,0]
	v_pk_mul_f32 v[132:133], v[84:85], v[136:137] op_sel_hi:[1,0]
	v_pk_mul_f32 v[138:139], v[94:95], v[136:137] op_sel_hi:[1,0]
	v_pk_mul_f32 v[136:137], v[92:93], v[136:137] op_sel_hi:[1,0]
	s_setprio 1
	s_waitcnt lgkmcnt(5)
; #define LAS __attribute__((address_space(3)))
; #define MFMA16(a, b, c) __builtin_amdgcn_mfma_f32_16x16x32_bf16((a), (b), (c), 0, 0, 0)
; DI u32x2 tr4(const LAS unsigned char* p) { return __builtin_bit_cast(u32x2, __builtin_amdgcn_ds_read_tr16_b64_v4i16((LAS v4i16_t*)p)); }
; DI void at_pv(AtState& S, const f32x4 (&s1)[4], const f32x4 (&s2)[4], float alpha, float ps1, float ps2, const LAS unsigned char* buf, int hh, int fq, int tq, int tp) {
;     ...
;     for (int dh = 0; dh < 2; ++dh) {
;         bf16x8 vt[2][2];
; #pragma unroll
;         for (int d2 = 0; d2 < 2; ++d2)
; #pragma unroll
;             for (int s = 0; s < 2; ++s) { const int dt = 2 * dh + d2; const LAS unsigned char* vr = buf + AT_V + (32 * s + 4 * fq + tq) * 288 + (hh * 64 + 16 * dt + 4 * tp) * 2; vt[d2][s] = cat44(tr4(vr), tr4(vr + 16 * 288)); }
;         __builtin_amdgcn_s_setprio(1);
; #pragma unroll
;         for (int s = 0; s < 2; ++s)
; #pragma unroll
;             for (int d2 = 0; d2 < 2; ++d2) { const int dt = 2 * dh + d2; S.O1[dt] = MFMA16(vt[d2][s], p1[s], S.O1[dt]); S.O2[dt] = MFMA16(vt[d2][s], p2[s], S.O2[dt]); }
;         __builtin_amdgcn_s_setprio(0);
;         __builtin_amdgcn_sched_barrier(0);
;     }
	v_mfma_f32_16x16x32_bf16 v[108:111], v[232:235], v[216:219], v[108:111]
	v_mfma_f32_16x16x32_bf16 v[112:115], v[232:235], v[220:223], v[112:115]
	s_waitcnt lgkmcnt(2)
	v_mfma_f32_16x16x32_bf16 v[232:235], v[236:239], v[216:219], v[116:119]
	v_mfma_f32_16x16x32_bf16 v[236:239], v[236:239], v[220:223], v[120:123]
	v_mfma_f32_16x16x32_bf16 v[120:123], v[240:243], v[224:227], v[108:111]
	v_mfma_f32_16x16x32_bf16 v[116:119], v[240:243], v[228:231], v[112:115]
	s_waitcnt lgkmcnt(0)
	v_mfma_f32_16x16x32_bf16 v[112:115], v[244:247], v[224:227], v[232:235]
	v_mfma_f32_16x16x32_bf16 v[108:111], v[244:247], v[228:231], v[236:239]
	s_setprio 0
	s_nop 0
	ds_read_b64_tr_b16 v[232:233], v208 offset:17472
	ds_read_b64_tr_b16 v[236:237], v208 offset:17504
	ds_read_b64_tr_b16 v[234:235], v208 offset:22080
	ds_read_b64_tr_b16 v[238:239], v208 offset:22112
	ds_read_b64_tr_b16 v[240:241], v208 offset:26688
	ds_read_b64_tr_b16 v[242:243], v208 offset:31296
	ds_read_b64_tr_b16 v[246:247], v208 offset:31328
	ds_read_b64_tr_b16 v[244:245], v208 offset:26720
	s_setprio 1
	s_waitcnt lgkmcnt(5)
	v_mfma_f32_16x16x32_bf16 v[124:127], v[232:235], v[216:219], v[124:127]
	v_mfma_f32_16x16x32_bf16 v[128:131], v[232:235], v[220:223], v[128:131]
	s_waitcnt lgkmcnt(4)
	v_mfma_f32_16x16x32_bf16 v[216:219], v[236:239], v[216:219], v[132:135]
	v_mfma_f32_16x16x32_bf16 v[220:223], v[236:239], v[220:223], v[136:139]
	s_waitcnt lgkmcnt(2)
	v_mfma_f32_16x16x32_bf16 v[136:139], v[240:243], v[224:227], v[124:127]
	v_mfma_f32_16x16x32_bf16 v[132:135], v[240:243], v[228:231], v[128:131]
	s_waitcnt lgkmcnt(0)
	v_mfma_f32_16x16x32_bf16 v[128:131], v[244:247], v[224:227], v[216:219]
	v_mfma_f32_16x16x32_bf16 v[124:127], v[244:247], v[228:231], v[220:223]
	s_setprio 0
	s_cbranch_execnz .LBB0_1380

; DI void lds_barrier() { asm volatile("s_waitcnt lgkmcnt(0)" ::: "memory"); __builtin_amdgcn_s_barrier(); asm volatile("" ::: "memory"); }
; template <int VAR>
; DI void attn_tile(AtState& S, const LAS unsigned char* buf, const bf16x8 q1, const bf16x8 q2, int kt, bool diag, int qpos0, int qpos_l, float slope2, float adv, float decay, int hh, int fr, int fq) {
;     ...
;         asm volatile("; attention: fast tile" ::: "memory");
;         at_qk(s1, s2, buf, q1, q2, S.cinit, hh, fr, fq);
;         S.ref += adv;
;         at_exp(s1, s2, ps1, ps2);
;         if (__any(!(ps1 + ps2 < 0x1p60f))) {
;             asm volatile("; attention: bump" ::: "memory");
;             at_qk(s1, s2, buf, q1, q2, S.cinit, hh, fr, fq);
;             float lm = -1e30f;
; #pragma unroll
;             for (int k4 = 0; k4 < 4; ++k4)
; #pragma unroll
;                 for (int j = 0; j < 4; ++j) lm = fmaxf(lm, fmaxf(s1[k4][j], s2[k4][j]));
;             lm = fmaxf(lm, __shfl_xor(lm, 16)); lm = fmaxf(lm, __shfl_xor(lm, 32));
; template <int VAR>
; DI void attn_segment(const Args& a, const Frame& F, int l, int qrow0, int qpos0, int hp, int ntile, int nf32, const float* ck, const float* cv, int prow0) {
;     ...
;         for (int kt = 0; kt < ntile; kt += 2) {
;             atb_issue(rb, pb + (size_t)(kt + 2 < nl ? kt + 2 : nl) * TSTR, voff);
;             attn_tile<VAR>(S, F.lds + (kt & 1) * AT_BUF, q1, q2, kt, kt + 1 == ntile, qpos0, qpos_l, slope2, adv, decay, hh, fr, fq);
;             atb_commit(ra, F.lds + ((kt + 1) & 1) * AT_BUF, tid);
;             lds_barrier();
;             if (kt + 1 >= ntile) break;
;             atb_issue(ra, pb + (size_t)(kt + 3 < nl ? kt + 3 : nl) * TSTR, voff);
;             attn_tile<VAR>(S, F.lds + ((kt + 1) & 1) * AT_BUF, q1, q2, kt + 1, kt + 2 == ntile, qpos0, qpos_l, slope2, adv, decay, hh, fr, fq);
.Lcommit_done_A:
	s_waitcnt lgkmcnt(0)
	s_barrier
	s_add_i32 s14, s26, -2
	s_cmp_ge_i32 s14, s24
	s_mov_b64 s[14:15], -1
	s_cbranch_scc1 .LBB0_1375
	s_min_i32 s14, s26, s25
	s_ashr_i32 s15, s14, 31
	s_lshl_b64 s[14:15], s[14:15], 18
	s_add_u32 s14, s0, s14
	s_addc_u32 s15, s1, s15
	v_lshl_add_u64 v[16:17], s[14:15], 0, v[144:145]
	v_lshl_add_u64 v[24:25], s[14:15], 0, v[146:147]
	global_load_dwordx4 v[12:15], v[16:17], off offset:1024
	s_nop 0
	global_load_dwordx4 v[16:19], v[16:17], off offset:1536
	s_nop 0
	global_load_dwordx4 v[20:23], v[24:25], off offset:1024
	s_nop 0
	global_load_dwordx4 v[24:27], v[24:25], off offset:1536
	s_cmpk_lg_i32 s28, 0x41
	s_mov_b64 s[14:15], -1
	s_cbranch_scc0 .LBB0_1391
	ds_read_b128 v[44:47], v213 offset:35840
	ds_read_b128 v[48:51], v213 offset:35904
	ds_read_b128 v[52:55], v213 offset:40192
	ds_read_b128 v[56:59], v213 offset:40256
	ds_read_b128 v[60:63], v213 offset:44544
	ds_read_b128 v[64:67], v213 offset:44608
	ds_read_b128 v[68:71], v213 offset:48896
	ds_read_b128 v[72:75], v213 offset:48960
	s_waitcnt lgkmcnt(7)
	v_mfma_f32_16x16x32_bf16 v[44:47], v[44:47], v[4:7], v[76:79]
	v_add_f32_e32 v215, v205, v3
	s_waitcnt lgkmcnt(6)
	v_mfma_f32_16x16x32_bf16 v[48:51], v[48:51], v[8:11], v[76:79]
	s_waitcnt lgkmcnt(5)
	v_mfma_f32_16x16x32_bf16 v[52:55], v[52:55], v[4:7], v[96:99]
	s_nop 2
	v_exp_f32_e32 v164, v44
	v_exp_f32_e32 v165, v45
	v_exp_f32_e32 v168, v46
	s_waitcnt lgkmcnt(4)
	v_mfma_f32_16x16x32_bf16 v[56:59], v[56:59], v[8:11], v[96:99]
	v_exp_f32_e32 v169, v47
	v_exp_f32_e32 v162, v48
	v_exp_f32_e32 v163, v49
	s_waitcnt lgkmcnt(3)
	v_mfma_f32_16x16x32_bf16 v[60:63], v[60:63], v[4:7], v[104:107]
	v_exp_f32_e32 v166, v50
	v_exp_f32_e32 v167, v51
	v_exp_f32_e32 v172, v52
	s_waitcnt lgkmcnt(2)
	v_mfma_f32_16x16x32_bf16 v[44:47], v[64:67], v[8:11], v[104:107]
	v_exp_f32_e32 v170, v56
	v_exp_f32_e32 v173, v53
	v_exp_f32_e32 v176, v54
	s_waitcnt lgkmcnt(1)
	v_mfma_f32_16x16x32_bf16 v[48:51], v[68:71], v[4:7], v[80:83]
	v_exp_f32_e32 v177, v55
	v_exp_f32_e32 v174, v58
	v_exp_f32_e32 v175, v59
	s_waitcnt lgkmcnt(0)
	v_mfma_f32_16x16x32_bf16 v[64:67], v[72:75], v[8:11], v[80:83]
	v_exp_f32_e32 v171, v57
	v_exp_f32_e32 v180, v60
	v_exp_f32_e32 v178, v44
	v_exp_f32_e32 v181, v61
	v_exp_f32_e32 v179, v45
	v_exp_f32_e32 v184, v62
	v_exp_f32_e32 v185, v63
	v_exp_f32_e32 v182, v46
	v_exp_f32_e32 v183, v47
	v_exp_f32_e32 v188, v48
	v_exp_f32_e32 v186, v64
	v_exp_f32_e32 v189, v49
	v_exp_f32_e32 v192, v50
	v_exp_f32_e32 v193, v51
	v_exp_f32_e32 v190, v66
	v_exp_f32_e32 v191, v67
	v_exp_f32_e32 v187, v65
	v_pk_add_f32 v[84:85], v[164:165], 0 op_sel_hi:[1,0]
	v_pk_add_f32 v[86:87], v[168:169], 0 op_sel_hi:[1,0]
	v_pk_add_f32 v[68:69], v[162:163], 0 op_sel_hi:[1,0]
	v_pk_add_f32 v[70:71], v[166:167], 0 op_sel_hi:[1,0]
	v_pk_add_f32 v[52:53], v[86:87], v[176:177]
	v_pk_add_f32 v[54:55], v[84:85], v[172:173]
	v_pk_add_f32 v[56:57], v[70:71], v[174:175]
	v_pk_add_f32 v[58:59], v[68:69], v[170:171]
	v_pk_add_f32 v[44:45], v[54:55], v[180:181]
	v_pk_add_f32 v[46:47], v[52:53], v[184:185]
	v_pk_add_f32 v[52:53], v[58:59], v[178:179]
	v_pk_add_f32 v[54:55], v[56:57], v[182:183]
	v_pk_add_f32 v[46:47], v[46:47], v[192:193]
	v_pk_add_f32 v[44:45], v[44:45], v[188:189]
	v_pk_add_f32 v[48:49], v[54:55], v[190:191]
	v_pk_add_f32 v[50:51], v[52:53], v[186:187]
	v_mov_b32_e32 v53, v44
	v_mov_b32_e32 v52, v50
	v_mov_b32_e32 v44, v51
	v_mov_b32_e32 v50, v48
	v_mov_b32_e32 v51, v46
	v_mov_b32_e32 v46, v49
	v_pk_add_f32 v[44:45], v[52:53], v[44:45]
	v_pk_add_f32 v[46:47], v[50:51], v[46:47]
	s_nop 0
	v_pk_add_f32 v[194:195], v[44:45], v[46:47]
	s_nop 0
	v_add_f32_e32 v44, v195, v194
	v_cmp_ngt_f32_e32 vcc, s65, v44
	s_cbranch_vccz .LBB0_1395
	ds_read_b128 v[44:47], v213 offset:35840
	ds_read_b128 v[48:51], v213 offset:35904
	ds_read_b128 v[52:55], v213 offset:40192
	ds_read_b128 v[56:59], v213 offset:40256
	ds_read_b128 v[60:63], v213 offset:44544
	ds_read_b128 v[64:67], v213 offset:44608
	ds_read_b128 v[68:71], v213 offset:48896
	ds_read_b128 v[72:75], v213 offset:48960
	s_waitcnt lgkmcnt(7)
	v_mfma_f32_16x16x32_bf16 v[44:47], v[44:47], v[4:7], v[76:79]
	s_waitcnt lgkmcnt(6)
	v_mfma_f32_16x16x32_bf16 v[48:51], v[48:51], v[8:11], v[76:79]
	s_waitcnt lgkmcnt(5)
	v_mfma_f32_16x16x32_bf16 v[52:55], v[52:55], v[4:7], v[96:99]
	s_waitcnt lgkmcnt(4)
	v_mfma_f32_16x16x32_bf16 v[56:59], v[56:59], v[8:11], v[96:99]
	s_waitcnt lgkmcnt(3)
	v_mfma_f32_16x16x32_bf16 v[60:63], v[60:63], v[4:7], v[104:107]
	s_waitcnt lgkmcnt(2)
	v_mfma_f32_16x16x32_bf16 v[64:67], v[64:67], v[8:11], v[104:107]
	s_waitcnt lgkmcnt(1)
	v_mfma_f32_16x16x32_bf16 v[68:71], v[68:71], v[4:7], v[80:83]
	s_waitcnt lgkmcnt(0)
	v_mfma_f32_16x16x32_bf16 v[72:75], v[72:75], v[8:11], v[80:83]
	v_max3_f32 v84, v44, v48, s60
	v_max3_f32 v84, v84, v45, v49
	v_max3_f32 v84, v84, v46, v50
	v_max3_f32 v84, v84, v47, v51
	v_max3_f32 v84, v84, v52, v56
	v_max3_f32 v84, v84, v53, v57
	v_max3_f32 v84, v84, v54, v58
	v_max3_f32 v84, v84, v55, v59
	v_max3_f32 v84, v84, v60, v64
	v_max3_f32 v84, v84, v61, v65
	v_max3_f32 v84, v84, v62, v66
	v_max3_f32 v84, v84, v63, v67
	v_max3_f32 v84, v84, v68, v72
	v_max3_f32 v84, v84, v69, v73
	v_max3_f32 v84, v84, v70, v74
	v_max3_f32 v84, v84, v71, v75
	v_and_b32_e32 v86, 64, v198
	v_mov_b32_e32 v85, v84
	v_mov_b32_e32 v255, v84
	s_nop 1
	v_permlane16_swap_b32_e32 v85, v255
	s_waitcnt lgkmcnt(0)
	v_max_f32_e32 v84, v85, v255
	v_mov_b32_e32 v85, v84
	v_mov_b32_e32 v255, v84
	s_nop 1
	v_permlane32_swap_b32_e32 v85, v255
	s_waitcnt lgkmcnt(0)
; #define LAS __attribute__((address_space(3)))
; DI float fast_exp2(float x) { return __builtin_amdgcn_exp2f(x); }
; DI u32x2 tr4(const LAS unsigned char* p) { return __builtin_bit_cast(u32x2, __builtin_amdgcn_ds_read_tr16_b64_v4i16((LAS v4i16_t*)p)); }
; DI bf16x8 packp(f32x4 a, f32x4 b) { return __builtin_bit_cast(bf16x8, pack8(a, b)); }
; DI void at_pv(AtState& S, const f32x4 (&s1)[4], const f32x4 (&s2)[4], float alpha, float ps1, float ps2, const LAS unsigned char* buf, int hh, int fq, int tq, int tp) {
;     S.l1 = S.l1 * alpha + ps1; S.l2 = S.l2 * alpha + ps2;
; #pragma unroll
;     for (int dt = 0; dt < 4; ++dt) { S.O1[dt] = S.O1[dt] * alpha; S.O2[dt] = S.O2[dt] * alpha; }
;     bf16x8 p1[2], p2[2];
; #pragma unroll
;     for (int s = 0; s < 2; ++s) { p1[s] = packp(s1[2 * s], s1[2 * s + 1]); p2[s] = packp(s2[2 * s], s2[2 * s + 1]); }
; #pragma unroll
;     for (int dh = 0; dh < 2; ++dh) {
;         bf16x8 vt[2][2];
; #pragma unroll
;         for (int d2 = 0; d2 < 2; ++d2)
; #pragma unroll
;             for (int s = 0; s < 2; ++s) { const int dt = 2 * dh + d2; const LAS unsigned char* vr = buf + AT_V + (32 * s + 4 * fq + tq) * 288 + (hh * 64 + 16 * dt + 4 * tp) * 2; vt[d2][s] = cat44(tr4(vr), tr4(vr + 16 * 288)); }
; template <int VAR>
; DI void attn_tile(AtState& S, const LAS unsigned char* buf, const bf16x8 q1, const bf16x8 q2, int kt, bool diag, int qpos0, int qpos_l, float slope2, float adv, float decay, int hh, int fr, int fq) {
;     ...
;             lm = fmaxf(lm, __shfl_xor(lm, 16)); lm = fmaxf(lm, __shfl_xor(lm, 32));
;             const float bump = fmaxf(lm, 0.f);
;             const float alpha = decay * fast_exp2(-bump); S.ref += bump;
; #pragma unroll
;             for (int k4 = 0; k4 < 4; ++k4) { s1[k4] = s1[k4] - bump; s2[k4] = s2[k4] - bump; S.cinit[k4] = S.cinit[k4] - bump; }
;             at_exp(s1, s2, ps1, ps2);
;             at_pv(S, s1, s2, alpha, ps1, ps2, buf, hh, fq, tq, tp);
	v_max3_f32 v84, v255, v85, 0
	v_sub_f32_e32 v86, v47, v84
	v_sub_f32_e32 v87, v46, v84
	v_sub_f32_e32 v88, v45, v84
	v_sub_f32_e32 v89, v44, v84
	v_sub_f32_e32 v90, v51, v84
	v_sub_f32_e32 v91, v50, v84
	v_sub_f32_e32 v92, v49, v84
	v_sub_f32_e32 v93, v48, v84
	v_sub_f32_e32 v94, v55, v84
	v_sub_f32_e32 v95, v54, v84
	v_sub_f32_e32 v101, v53, v84
	v_sub_f32_e32 v102, v52, v84
	v_sub_f32_e32 v103, v59, v84
	v_sub_f32_e32 v151, v58, v84
	v_sub_f32_e32 v156, v57, v84
	v_sub_f32_e32 v157, v56, v84
	v_exp_f32_e32 v216, v89
	v_exp_f32_e32 v220, v93
	v_exp_f32_e32 v217, v88
	v_exp_f32_e32 v221, v92
	v_exp_f32_e32 v218, v87
	v_exp_f32_e32 v222, v91
	v_exp_f32_e32 v219, v86
	v_exp_f32_e32 v223, v90
	v_sub_f32_e32 v237, v63, v84
	v_sub_f32_e32 v236, v62, v84
	v_sub_f32_e32 v233, v61, v84
	v_sub_f32_e32 v232, v60, v84
	v_sub_f32_e32 v239, v67, v84
	v_sub_f32_e32 v238, v66, v84
	v_sub_f32_e32 v235, v65, v84
	v_sub_f32_e32 v234, v64, v84
	v_exp_f32_e32 v224, v102
	v_exp_f32_e32 v226, v157
	v_exp_f32_e32 v225, v101
	v_exp_f32_e32 v227, v156
	v_exp_f32_e32 v228, v95
	v_exp_f32_e32 v230, v151
	v_exp_f32_e32 v229, v94
	v_exp_f32_e32 v231, v103
	v_sub_f32_e32 v71, v71, v84
	v_sub_f32_e32 v70, v70, v84
	v_sub_f32_e32 v69, v69, v84
	v_sub_f32_e32 v68, v68, v84
	v_sub_f32_e32 v75, v75, v84
	v_sub_f32_e32 v74, v74, v84
	v_sub_f32_e32 v73, v73, v84
	v_sub_f32_e32 v72, v72, v84
	v_exp_f32_e32 v232, v232
	v_exp_f32_e32 v234, v234
	v_exp_f32_e32 v233, v233
	v_exp_f32_e32 v235, v235
	v_exp_f32_e32 v236, v236
	v_exp_f32_e32 v238, v238
	v_exp_f32_e32 v237, v237
	v_exp_f32_e32 v239, v239
	v_exp_f32_e32 v240, v68
	v_exp_f32_e32 v242, v72
	v_exp_f32_e32 v241, v69
	v_exp_f32_e32 v243, v73
	v_exp_f32_e32 v244, v70
	v_exp_f32_e32 v246, v74
	v_exp_f32_e32 v245, v71
	v_exp_f32_e32 v247, v75
	v_pk_add_f32 v[60:61], v[216:217], 0 op_sel_hi:[1,0]
	v_pk_add_f32 v[62:63], v[218:219], 0 op_sel_hi:[1,0]
	v_pk_add_f32 v[64:65], v[220:221], 0 op_sel_hi:[1,0]
	v_pk_add_f32 v[66:67], v[222:223], 0 op_sel_hi:[1,0]
	v_pk_add_f32 v[62:63], v[228:229], v[62:63]
	v_pk_add_f32 v[60:61], v[224:225], v[60:61]
	v_pk_add_f32 v[66:67], v[230:231], v[66:67]
	v_pk_add_f32 v[64:65], v[226:227], v[64:65]
	v_pk_add_f32 v[60:61], v[232:233], v[60:61]
	v_pk_add_f32 v[62:63], v[236:237], v[62:63]
	v_pk_add_f32 v[64:65], v[234:235], v[64:65]
	v_pk_add_f32 v[66:67], v[238:239], v[66:67]
	v_pk_add_f32 v[62:63], v[244:245], v[62:63]
	v_pk_add_f32 v[60:61], v[240:241], v[60:61]
	v_pk_add_f32 v[66:67], v[246:247], v[66:67]
	v_pk_add_f32 v[64:65], v[242:243], v[64:65]
	v_cvt_pk_bf16_f32 v216, v216, v217
	v_cvt_pk_bf16_f32 v217, v218, v219
	v_cvt_pk_bf16_f32 v218, v224, v225
	v_cvt_pk_bf16_f32 v219, v228, v229
	v_cvt_pk_bf16_f32 v220, v220, v221
	v_cvt_pk_bf16_f32 v221, v222, v223
	v_cvt_pk_bf16_f32 v222, v226, v227
	v_cvt_pk_bf16_f32 v223, v230, v231
	v_cvt_pk_bf16_f32 v224, v232, v233
	v_cvt_pk_bf16_f32 v225, v236, v237
	v_cvt_pk_bf16_f32 v226, v240, v241
	v_cvt_pk_bf16_f32 v227, v244, v245
	v_cvt_pk_bf16_f32 v228, v234, v235
	v_cvt_pk_bf16_f32 v229, v238, v239
	v_cvt_pk_bf16_f32 v230, v242, v243
	v_cvt_pk_bf16_f32 v231, v246, v247
	ds_read_b64_tr_b16 v[232:233], v208 offset:53248
	ds_read_b64_tr_b16 v[236:237], v208 offset:53280
	ds_read_b64_tr_b16 v[234:235], v208 offset:57856
	ds_read_b64_tr_b16 v[240:241], v208 offset:62464
	ds_read_b64_tr_b16 v[242:243], v209 offset:4608
	ds_read_b64_tr_b16 v[238:239], v208 offset:57888
	ds_read_b64_tr_b16 v[244:245], v208 offset:62496
	ds_read_b64_tr_b16 v[246:247], v210 offset:4608
	v_exp_f32_e64 v85, -v84
	v_mov_b32_e32 v68, v64
	v_mov_b32_e32 v69, v60
	v_mov_b32_e32 v60, v65
	v_mov_b32_e32 v64, v66
	v_mov_b32_e32 v65, v62
	v_mov_b32_e32 v62, v67
	v_pk_add_f32 v[60:61], v[68:69], v[60:61]
	v_pk_add_f32 v[62:63], v[64:65], v[62:63]
	v_mul_f32_e32 v100, v150, v85
	v_pk_add_f32 v[60:61], v[60:61], v[62:63]
	v_add_f32_e32 v214, v215, v84
	v_sub_f32_e32 v47, v79, v84
	v_sub_f32_e32 v46, v78, v84
	v_sub_f32_e32 v45, v77, v84
	v_sub_f32_e32 v44, v76, v84
	v_sub_f32_e32 v51, v99, v84
	v_sub_f32_e32 v50, v98, v84
	v_sub_f32_e32 v49, v97, v84
	v_sub_f32_e32 v48, v96, v84
	v_sub_f32_e32 v55, v107, v84
	v_sub_f32_e32 v54, v106, v84
	v_sub_f32_e32 v53, v105, v84
	v_sub_f32_e32 v52, v104, v84
	v_sub_f32_e32 v59, v83, v84
	v_sub_f32_e32 v58, v82, v84
	v_sub_f32_e32 v57, v81, v84
	v_sub_f32_e32 v56, v80, v84
	v_pk_fma_f32 v[156:157], v[158:159], v[100:101], v[60:61] op_sel_hi:[1,0,1]
	v_pk_mul_f32 v[62:63], v[122:123], v[100:101] op_sel_hi:[1,0]
	v_pk_mul_f32 v[60:61], v[120:121], v[100:101] op_sel_hi:[1,0]
	v_pk_mul_f32 v[66:67], v[118:119], v[100:101] op_sel_hi:[1,0]
	v_pk_mul_f32 v[64:65], v[116:117], v[100:101] op_sel_hi:[1,0]
	v_pk_mul_f32 v[70:71], v[114:115], v[100:101] op_sel_hi:[1,0]
	v_pk_mul_f32 v[68:69], v[112:113], v[100:101] op_sel_hi:[1,0]
	v_pk_mul_f32 v[74:75], v[110:111], v[100:101] op_sel_hi:[1,0]
	v_pk_mul_f32 v[72:73], v[108:109], v[100:101] op_sel_hi:[1,0]
	v_pk_mul_f32 v[86:87], v[138:139], v[100:101] op_sel_hi:[1,0]
	v_pk_mul_f32 v[84:85], v[136:137], v[100:101] op_sel_hi:[1,0]
	v_pk_mul_f32 v[90:91], v[134:135], v[100:101] op_sel_hi:[1,0]
	v_pk_mul_f32 v[88:89], v[132:133], v[100:101] op_sel_hi:[1,0]
	v_pk_mul_f32 v[94:95], v[130:131], v[100:101] op_sel_hi:[1,0]
	v_pk_mul_f32 v[92:93], v[128:129], v[100:101] op_sel_hi:[1,0]
	v_pk_mul_f32 v[102:103], v[126:127], v[100:101] op_sel_hi:[1,0]
	v_pk_mul_f32 v[100:101], v[124:125], v[100:101] op_sel_hi:[1,0]
	s_setprio 1
	s_waitcnt lgkmcnt(5)
; #define LAS __attribute__((address_space(3)))
; #define MFMA16(a, b, c) __builtin_amdgcn_mfma_f32_16x16x32_bf16((a), (b), (c), 0, 0, 0)
; DI u32x2 tr4(const LAS unsigned char* p) { return __builtin_bit_cast(u32x2, __builtin_amdgcn_ds_read_tr16_b64_v4i16((LAS v4i16_t*)p)); }
; DI void at_pv(AtState& S, const f32x4 (&s1)[4], const f32x4 (&s2)[4], float alpha, float ps1, float ps2, const LAS unsigned char* buf, int hh, int fq, int tq, int tp) {
;     ...
;     for (int dh = 0; dh < 2; ++dh) {
;         bf16x8 vt[2][2];
; #pragma unroll
;         for (int d2 = 0; d2 < 2; ++d2)
; #pragma unroll
;             for (int s = 0; s < 2; ++s) { const int dt = 2 * dh + d2; const LAS unsigned char* vr = buf + AT_V + (32 * s + 4 * fq + tq) * 288 + (hh * 64 + 16 * dt + 4 * tp) * 2; vt[d2][s] = cat44(tr4(vr), tr4(vr + 16 * 288)); }
;         __builtin_amdgcn_s_setprio(1);
; #pragma unroll
;         for (int s = 0; s < 2; ++s)
; #pragma unroll
;             for (int d2 = 0; d2 < 2; ++d2) { const int dt = 2 * dh + d2; S.O1[dt] = MFMA16(vt[d2][s], p1[s], S.O1[dt]); S.O2[dt] = MFMA16(vt[d2][s], p2[s], S.O2[dt]); }
;         __builtin_amdgcn_s_setprio(0);
;         __builtin_amdgcn_sched_barrier(0);
;     }
	v_mfma_f32_16x16x32_bf16 v[60:63], v[232:235], v[216:219], v[60:63]
	v_mfma_f32_16x16x32_bf16 v[232:235], v[232:235], v[220:223], v[64:67]
	s_waitcnt lgkmcnt(2)
	v_mfma_f32_16x16x32_bf16 v[68:71], v[236:239], v[216:219], v[68:71]
	v_mfma_f32_16x16x32_bf16 v[236:239], v[236:239], v[220:223], v[72:75]
	v_mfma_f32_16x16x32_bf16 v[64:67], v[240:243], v[224:227], v[60:63]
	v_mfma_f32_16x16x32_bf16 v[72:75], v[240:243], v[228:231], v[232:235]
	s_waitcnt lgkmcnt(0)
	v_mfma_f32_16x16x32_bf16 v[60:63], v[244:247], v[224:227], v[68:71]
	v_mfma_f32_16x16x32_bf16 v[68:71], v[244:247], v[228:231], v[236:239]
	s_setprio 0
	ds_read_b64_tr_b16 v[232:233], v208 offset:53312
	s_nop 0
	ds_read_b64_tr_b16 v[236:237], v208 offset:53344
	ds_read_b64_tr_b16 v[234:235], v208 offset:57920
	ds_read_b64_tr_b16 v[238:239], v208 offset:57952
	ds_read_b64_tr_b16 v[240:241], v208 offset:62528
	ds_read_b64_tr_b16 v[242:243], v211 offset:4608
	ds_read_b64_tr_b16 v[246:247], v212 offset:4608
	ds_read_b64_tr_b16 v[244:245], v208 offset:62560
	s_setprio 1
	s_waitcnt lgkmcnt(5)
	v_mfma_f32_16x16x32_bf16 v[84:87], v[232:235], v[216:219], v[84:87]
	v_mfma_f32_16x16x32_bf16 v[232:235], v[232:235], v[220:223], v[88:91]
	s_waitcnt lgkmcnt(4)
	v_mfma_f32_16x16x32_bf16 v[92:95], v[236:239], v[216:219], v[92:95]
	v_mfma_f32_16x16x32_bf16 v[216:219], v[236:239], v[220:223], v[100:103]
	s_waitcnt lgkmcnt(2)
	v_mfma_f32_16x16x32_bf16 v[88:91], v[240:243], v[224:227], v[84:87]
	v_mfma_f32_16x16x32_bf16 v[100:103], v[240:243], v[228:231], v[232:235]
	s_waitcnt lgkmcnt(0)
	v_mfma_f32_16x16x32_bf16 v[84:87], v[244:247], v[224:227], v[92:95]
	v_mfma_f32_16x16x32_bf16 v[92:95], v[244:247], v[228:231], v[216:219]
	s_setprio 0
	s_cbranch_execnz .LBB0_1390

; #define LAS __attribute__((address_space(3)))
; DI float fast_exp2(float x) { return __builtin_amdgcn_exp2f(x); }
; #define MFMA16(a, b, c) __builtin_amdgcn_mfma_f32_16x16x32_bf16((a), (b), (c), 0, 0, 0)
; DI void at_qk(f32x4 (&s1)[4], f32x4 (&s2)[4], const LAS unsigned char* buf, const bf16x8 q1, const bf16x8 q2, const f32x4 (&ci)[4], int hh, int fr, int fq) {
; #pragma unroll
;     for (int k4 = 0; k4 < 4; ++k4) { const LAS unsigned char* kr = buf + AT_K + (16 * k4 + fr) * 272 + hh * 128 + fq * 16;
;         s1[k4] = MFMA16(ld8l(kr), q1, ci[k4]); s2[k4] = MFMA16(ld8l(kr + 64), q2, ci[k4]); }
; }
; DI void at_exp(f32x4 (&s1)[4], f32x4 (&s2)[4], float& ps1, float& ps2) {
;     f32x4 a1 = (f32x4){0.f, 0.f, 0.f, 0.f}, a2 = a1;
; #pragma unroll
;     for (int k4 = 0; k4 < 4; ++k4) {
; #pragma unroll
;         for (int j = 0; j < 4; ++j) { s1[k4][j] = fast_exp2(s1[k4][j]); s2[k4][j] = fast_exp2(s2[k4][j]); }
;         a1 = a1 + s1[k4]; a2 = a2 + s2[k4]; }
;     ps1 = (a1[0] + a1[1]) + (a1[2] + a1[3]); ps2 = (a2[0] + a2[1]) + (a2[2] + a2[3]);
; }
; template <int VAR>
; DI void attn_tile(AtState& S, const LAS unsigned char* buf, const bf16x8 q1, const bf16x8 q2, int kt, bool diag, int qpos0, int qpos_l, float slope2, float adv, float decay, int hh, int fr, int fq) {
;     ...
;         at_qk(s1, s2, buf, q1, q2, S.cinit, hh, fr, fq);
;         S.ref += adv;
;         at_exp(s1, s2, ps1, ps2);
;         if (__any(!(ps1 + ps2 < 0x1p60f))) {
;             asm volatile("; attention: bump" ::: "memory");
;             at_qk(s1, s2, buf, q1, q2, S.cinit, hh, fr, fq);
;             float lm = -1e30f;
; #pragma unroll
;             for (int k4 = 0; k4 < 4; ++k4)
; #pragma unroll
;                 for (int j = 0; j < 4; ++j) lm = fmaxf(lm, fmaxf(s1[k4][j], s2[k4][j]));
;             lm = fmaxf(lm, __shfl_xor(lm, 16)); lm = fmaxf(lm, __shfl_xor(lm, 32));
.LBB0_1405:
	s_bitcmp1_b32 s40, 0
	s_cselect_b32 s26, 0x8c00, 0
	s_add_i32 s28, s41, s26
	s_sub_i32 s27, s40, 32
	v_add_u32_e32 v3, s28, v206
	s_cmp_gt_u32 s27, 0xffffffe0
	s_mov_b64 s[26:27], -1
	v_add_u32_e32 v3, v3, v207
	s_cbranch_scc0 .LBB0_1410
	ds_read_b128 v[62:65], v3
	ds_read_b128 v[66:69], v3 offset:64
	ds_read_b128 v[70:73], v3 offset:4352
	ds_read_b128 v[74:77], v3 offset:4416
	ds_read_b128 v[78:81], v3 offset:8704
	ds_read_b128 v[82:85], v3 offset:8768
	ds_read_b128 v[86:89], v3 offset:13056
	ds_read_b128 v[90:93], v3 offset:13120
	s_waitcnt lgkmcnt(7)
	v_mfma_f32_16x16x32_bf16 v[62:65], v[62:65], v[38:41], v[46:49]
	v_add_f32_e32 v213, v204, v212
	s_waitcnt lgkmcnt(6)
	v_mfma_f32_16x16x32_bf16 v[66:69], v[66:69], v[42:45], v[46:49]
	s_waitcnt lgkmcnt(5)
	v_mfma_f32_16x16x32_bf16 v[70:73], v[70:73], v[38:41], v[50:53]
	s_nop 2
	v_exp_f32_e32 v164, v62
	v_exp_f32_e32 v165, v63
	v_exp_f32_e32 v168, v64
	s_waitcnt lgkmcnt(4)
	v_mfma_f32_16x16x32_bf16 v[74:77], v[74:77], v[42:45], v[50:53]
	v_exp_f32_e32 v169, v65
	v_exp_f32_e32 v162, v66
	v_exp_f32_e32 v163, v67
	s_waitcnt lgkmcnt(3)
	v_mfma_f32_16x16x32_bf16 v[78:81], v[78:81], v[38:41], v[54:57]
	v_exp_f32_e32 v166, v68
	v_exp_f32_e32 v167, v69
	v_exp_f32_e32 v172, v70
	s_waitcnt lgkmcnt(2)
	v_mfma_f32_16x16x32_bf16 v[62:65], v[82:85], v[42:45], v[54:57]
	v_exp_f32_e32 v170, v74
	v_exp_f32_e32 v173, v71
	v_exp_f32_e32 v176, v72
	s_waitcnt lgkmcnt(1)
	v_mfma_f32_16x16x32_bf16 v[66:69], v[86:89], v[38:41], v[58:61]
	v_exp_f32_e32 v177, v73
	v_exp_f32_e32 v174, v76
	v_exp_f32_e32 v175, v77
	s_waitcnt lgkmcnt(0)
	v_mfma_f32_16x16x32_bf16 v[82:85], v[90:93], v[42:45], v[58:61]
	v_exp_f32_e32 v171, v75
	v_exp_f32_e32 v180, v78
	v_exp_f32_e32 v178, v62
	v_exp_f32_e32 v181, v79
	v_exp_f32_e32 v179, v63
	v_exp_f32_e32 v184, v80
	v_exp_f32_e32 v185, v81
	v_exp_f32_e32 v182, v64
	v_exp_f32_e32 v183, v65
	v_exp_f32_e32 v188, v66
	v_exp_f32_e32 v186, v82
	v_exp_f32_e32 v189, v67
	v_exp_f32_e32 v192, v68
	v_exp_f32_e32 v193, v69
	v_exp_f32_e32 v190, v84
	v_exp_f32_e32 v191, v85
	v_exp_f32_e32 v187, v83
	v_pk_add_f32 v[94:95], v[164:165], 0 op_sel_hi:[1,0]
	v_pk_add_f32 v[96:97], v[168:169], 0 op_sel_hi:[1,0]
	v_pk_add_f32 v[86:87], v[162:163], 0 op_sel_hi:[1,0]
	v_pk_add_f32 v[88:89], v[166:167], 0 op_sel_hi:[1,0]
	v_pk_add_f32 v[70:71], v[96:97], v[176:177]
	v_pk_add_f32 v[72:73], v[94:95], v[172:173]
	v_pk_add_f32 v[74:75], v[88:89], v[174:175]
	v_pk_add_f32 v[76:77], v[86:87], v[170:171]
	v_pk_add_f32 v[62:63], v[72:73], v[180:181]
	v_pk_add_f32 v[64:65], v[70:71], v[184:185]
	v_pk_add_f32 v[70:71], v[76:77], v[178:179]
	v_pk_add_f32 v[72:73], v[74:75], v[182:183]
	v_pk_add_f32 v[64:65], v[64:65], v[192:193]
	v_pk_add_f32 v[62:63], v[62:63], v[188:189]
	v_pk_add_f32 v[66:67], v[72:73], v[190:191]
	v_pk_add_f32 v[68:69], v[70:71], v[186:187]
	v_mov_b32_e32 v71, v62
	v_mov_b32_e32 v70, v68
	v_mov_b32_e32 v62, v69
	v_mov_b32_e32 v68, v66
	v_mov_b32_e32 v69, v64
	v_mov_b32_e32 v64, v67
	v_pk_add_f32 v[62:63], v[70:71], v[62:63]
	v_pk_add_f32 v[64:65], v[68:69], v[64:65]
	s_nop 0
	v_pk_add_f32 v[194:195], v[62:63], v[64:65]
	s_nop 0
	v_add_f32_e32 v62, v195, v194
	v_cmp_ngt_f32_e32 vcc, s65, v62
	s_cbranch_vccz .LBB0_1416
	ds_read_b128 v[62:65], v3
	ds_read_b128 v[66:69], v3 offset:64
	ds_read_b128 v[70:73], v3 offset:4352
	ds_read_b128 v[74:77], v3 offset:4416
	ds_read_b128 v[78:81], v3 offset:8704
	ds_read_b128 v[82:85], v3 offset:8768
	ds_read_b128 v[86:89], v3 offset:13056
	ds_read_b128 v[90:93], v3 offset:13120
	v_add3_u32 v246, s28, v208, v209
	s_waitcnt lgkmcnt(7)
	v_mfma_f32_16x16x32_bf16 v[62:65], v[62:65], v[38:41], v[46:49]
	s_waitcnt lgkmcnt(6)
	v_mfma_f32_16x16x32_bf16 v[66:69], v[66:69], v[42:45], v[46:49]
	s_waitcnt lgkmcnt(5)
	v_mfma_f32_16x16x32_bf16 v[70:73], v[70:73], v[38:41], v[50:53]
	s_waitcnt lgkmcnt(4)
	v_mfma_f32_16x16x32_bf16 v[74:77], v[74:77], v[42:45], v[50:53]
	s_waitcnt lgkmcnt(3)
	v_mfma_f32_16x16x32_bf16 v[78:81], v[78:81], v[38:41], v[54:57]
	s_waitcnt lgkmcnt(2)
	v_mfma_f32_16x16x32_bf16 v[82:85], v[82:85], v[42:45], v[54:57]
	s_waitcnt lgkmcnt(1)
	v_mfma_f32_16x16x32_bf16 v[86:89], v[86:89], v[38:41], v[58:61]
	s_waitcnt lgkmcnt(0)
	v_mfma_f32_16x16x32_bf16 v[90:93], v[90:93], v[42:45], v[58:61]
	v_max3_f32 v94, v62, v66, s60
	v_max3_f32 v94, v94, v63, v67
	v_max3_f32 v94, v94, v64, v68
	v_max3_f32 v94, v94, v65, v69
	v_max3_f32 v94, v94, v70, v74
	v_max3_f32 v94, v94, v71, v75
	v_max3_f32 v94, v94, v72, v76
	v_max3_f32 v94, v94, v73, v77
	v_max3_f32 v94, v94, v78, v82
	v_max3_f32 v94, v94, v79, v83
	v_max3_f32 v94, v94, v80, v84
	v_max3_f32 v94, v94, v81, v85
	v_max3_f32 v94, v94, v86, v90
	v_max3_f32 v94, v94, v87, v91
	v_max3_f32 v94, v94, v88, v92
	v_max3_f32 v94, v94, v89, v93
	v_and_b32_e32 v96, 64, v198
	v_mov_b32_e32 v95, v94
	v_mov_b32_e32 v255, v94
	s_nop 1
	v_permlane16_swap_b32_e32 v95, v255
	s_waitcnt lgkmcnt(0)
	v_max_f32_e32 v94, v95, v255
	v_mov_b32_e32 v95, v94
	v_mov_b32_e32 v255, v94
	s_nop 1
	v_permlane32_swap_b32_e32 v95, v255
	s_waitcnt lgkmcnt(0)
; #define LAS __attribute__((address_space(3)))
; DI float fast_exp2(float x) { return __builtin_amdgcn_exp2f(x); }
; DI u32x2 tr4(const LAS unsigned char* p) { return __builtin_bit_cast(u32x2, __builtin_amdgcn_ds_read_tr16_b64_v4i16((LAS v4i16_t*)p)); }
; DI bf16x8 packp(f32x4 a, f32x4 b) { return __builtin_bit_cast(bf16x8, pack8(a, b)); }
; DI void at_pv(AtState& S, const f32x4 (&s1)[4], const f32x4 (&s2)[4], float alpha, float ps1, float ps2, const LAS unsigned char* buf, int hh, int fq, int tq, int tp) {
;     S.l1 = S.l1 * alpha + ps1; S.l2 = S.l2 * alpha + ps2;
; #pragma unroll
;     for (int dt = 0; dt < 4; ++dt) { S.O1[dt] = S.O1[dt] * alpha; S.O2[dt] = S.O2[dt] * alpha; }
;     bf16x8 p1[2], p2[2];
; #pragma unroll
;     for (int s = 0; s < 2; ++s) { p1[s] = packp(s1[2 * s], s1[2 * s + 1]); p2[s] = packp(s2[2 * s], s2[2 * s + 1]); }
; #pragma unroll
;     for (int dh = 0; dh < 2; ++dh) {
;         bf16x8 vt[2][2];
; #pragma unroll
;         for (int d2 = 0; d2 < 2; ++d2)
; #pragma unroll
;             for (int s = 0; s < 2; ++s) { const int dt = 2 * dh + d2; const LAS unsigned char* vr = buf + AT_V + (32 * s + 4 * fq + tq) * 288 + (hh * 64 + 16 * dt + 4 * tp) * 2; vt[d2][s] = cat44(tr4(vr), tr4(vr + 16 * 288)); }
; template <int VAR>
; DI void attn_tile(AtState& S, const LAS unsigned char* buf, const bf16x8 q1, const bf16x8 q2, int kt, bool diag, int qpos0, int qpos_l, float slope2, float adv, float decay, int hh, int fr, int fq) {
;     ...
;             lm = fmaxf(lm, __shfl_xor(lm, 16)); lm = fmaxf(lm, __shfl_xor(lm, 32));
;             const float bump = fmaxf(lm, 0.f);
;             const float alpha = decay * fast_exp2(-bump); S.ref += bump;
; #pragma unroll
;             for (int k4 = 0; k4 < 4; ++k4) { s1[k4] = s1[k4] - bump; s2[k4] = s2[k4] - bump; S.cinit[k4] = S.cinit[k4] - bump; }
;             at_exp(s1, s2, ps1, ps2);
;             at_pv(S, s1, s2, alpha, ps1, ps2, buf, hh, fq, tq, tp);
	v_max3_f32 v94, v255, v95, 0
	v_sub_f32_e32 v96, v65, v94
	v_sub_f32_e32 v97, v64, v94
	v_sub_f32_e32 v98, v63, v94
	v_sub_f32_e32 v99, v62, v94
	v_sub_f32_e32 v69, v69, v94
	v_sub_f32_e32 v68, v68, v94
	v_sub_f32_e32 v67, v67, v94
	v_sub_f32_e32 v66, v66, v94
	v_sub_f32_e32 v100, v73, v94
	v_sub_f32_e32 v101, v72, v94
	v_sub_f32_e32 v102, v71, v94
	v_sub_f32_e32 v103, v70, v94
	v_sub_f32_e32 v104, v77, v94
	v_sub_f32_e32 v105, v76, v94
	v_sub_f32_e32 v107, v75, v94
	v_sub_f32_e32 v108, v74, v94
	v_exp_f32_e32 v214, v99
	v_exp_f32_e32 v218, v66
	v_exp_f32_e32 v215, v98
	v_exp_f32_e32 v219, v67
	v_exp_f32_e32 v216, v97
	v_exp_f32_e32 v220, v68
	v_exp_f32_e32 v217, v96
	v_exp_f32_e32 v221, v69
	v_sub_f32_e32 v109, v81, v94
	v_sub_f32_e32 v158, v80, v94
	v_sub_f32_e32 v159, v79, v94
	v_sub_f32_e32 v230, v78, v94
	v_sub_f32_e32 v85, v85, v94
	v_sub_f32_e32 v84, v84, v94
	v_sub_f32_e32 v83, v83, v94
	v_sub_f32_e32 v82, v82, v94
	v_exp_f32_e32 v222, v103
	v_exp_f32_e32 v224, v108
	v_exp_f32_e32 v223, v102
	v_exp_f32_e32 v225, v107
	v_exp_f32_e32 v226, v101
	v_exp_f32_e32 v228, v105
	v_exp_f32_e32 v227, v100
	v_exp_f32_e32 v229, v104
	v_sub_f32_e32 v89, v89, v94
	v_sub_f32_e32 v88, v88, v94
	v_sub_f32_e32 v87, v87, v94
	v_sub_f32_e32 v86, v86, v94
	v_sub_f32_e32 v245, v93, v94
	v_sub_f32_e32 v243, v92, v94
	v_sub_f32_e32 v241, v91, v94
	v_sub_f32_e32 v239, v90, v94
	v_exp_f32_e32 v230, v230
	v_exp_f32_e32 v232, v82
	v_exp_f32_e32 v231, v159
	v_exp_f32_e32 v233, v83
	v_exp_f32_e32 v234, v158
	v_exp_f32_e32 v236, v84
	v_exp_f32_e32 v235, v109
	v_exp_f32_e32 v237, v85
	v_exp_f32_e32 v238, v86
	v_exp_f32_e32 v240, v239
	v_exp_f32_e32 v239, v87
	v_exp_f32_e32 v241, v241
	v_exp_f32_e32 v242, v88
	v_exp_f32_e32 v244, v243
	v_exp_f32_e32 v243, v89
	v_exp_f32_e32 v245, v245
	v_pk_add_f32 v[66:67], v[214:215], 0 op_sel_hi:[1,0]
	v_pk_add_f32 v[68:69], v[216:217], 0 op_sel_hi:[1,0]
	v_pk_add_f32 v[70:71], v[218:219], 0 op_sel_hi:[1,0]
	v_pk_add_f32 v[72:73], v[220:221], 0 op_sel_hi:[1,0]
	v_pk_add_f32 v[68:69], v[226:227], v[68:69]
	v_pk_add_f32 v[66:67], v[222:223], v[66:67]
	v_pk_add_f32 v[72:73], v[228:229], v[72:73]
	v_pk_add_f32 v[70:71], v[224:225], v[70:71]
	v_pk_add_f32 v[66:67], v[230:231], v[66:67]
	v_pk_add_f32 v[68:69], v[234:235], v[68:69]
	v_pk_add_f32 v[70:71], v[232:233], v[70:71]
	v_pk_add_f32 v[72:73], v[236:237], v[72:73]
	v_pk_add_f32 v[68:69], v[242:243], v[68:69]
	v_pk_add_f32 v[66:67], v[238:239], v[66:67]
	v_pk_add_f32 v[72:73], v[244:245], v[72:73]
	v_pk_add_f32 v[70:71], v[240:241], v[70:71]
	v_cvt_pk_bf16_f32 v214, v214, v215
	v_cvt_pk_bf16_f32 v215, v216, v217
	v_cvt_pk_bf16_f32 v216, v222, v223
	v_cvt_pk_bf16_f32 v217, v226, v227
	v_cvt_pk_bf16_f32 v218, v218, v219
	v_cvt_pk_bf16_f32 v219, v220, v221
	v_cvt_pk_bf16_f32 v220, v224, v225
	v_cvt_pk_bf16_f32 v221, v228, v229
	v_cvt_pk_bf16_f32 v222, v230, v231
	v_cvt_pk_bf16_f32 v223, v234, v235
	v_cvt_pk_bf16_f32 v224, v238, v239
	v_cvt_pk_bf16_f32 v225, v242, v243
	v_cvt_pk_bf16_f32 v226, v232, v233
	v_cvt_pk_bf16_f32 v227, v236, v237
	v_cvt_pk_bf16_f32 v228, v240, v241
	v_cvt_pk_bf16_f32 v229, v244, v245
	ds_read_b64_tr_b16 v[230:231], v246 offset:17408
	ds_read_b64_tr_b16 v[234:235], v246 offset:17440
	ds_read_b64_tr_b16 v[232:233], v246 offset:22016
	ds_read_b64_tr_b16 v[238:239], v246 offset:26624
	ds_read_b64_tr_b16 v[240:241], v246 offset:31232
	ds_read_b64_tr_b16 v[236:237], v246 offset:22048
	ds_read_b64_tr_b16 v[242:243], v246 offset:26656
	ds_read_b64_tr_b16 v[244:245], v246 offset:31264
	v_exp_f32_e64 v95, -v94
	v_mov_b32_e32 v82, v70
	v_mov_b32_e32 v83, v66
	v_mov_b32_e32 v66, v71
	v_mov_b32_e32 v70, v72
	v_mov_b32_e32 v71, v68
	v_mov_b32_e32 v68, v73
	v_pk_add_f32 v[66:67], v[82:83], v[66:67]
	v_pk_add_f32 v[68:69], v[70:71], v[68:69]
	v_mul_f32_e32 v106, v116, v95
	v_pk_add_f32 v[66:67], v[66:67], v[68:69]
	v_add_f32_e32 v117, v213, v94
	v_sub_f32_e32 v65, v49, v94
	v_sub_f32_e32 v64, v48, v94
	v_sub_f32_e32 v63, v47, v94
	v_sub_f32_e32 v62, v46, v94
	v_sub_f32_e32 v77, v53, v94
	v_sub_f32_e32 v76, v52, v94
	v_sub_f32_e32 v75, v51, v94
	v_sub_f32_e32 v74, v50, v94
	v_sub_f32_e32 v81, v57, v94
	v_sub_f32_e32 v80, v56, v94
	v_sub_f32_e32 v79, v55, v94
	v_sub_f32_e32 v78, v54, v94
	v_sub_f32_e32 v93, v61, v94
	v_sub_f32_e32 v92, v60, v94
	v_sub_f32_e32 v91, v59, v94
	v_sub_f32_e32 v90, v58, v94
	v_pk_fma_f32 v[158:159], v[156:157], v[106:107], v[66:67] op_sel_hi:[1,0,1]
	v_pk_mul_f32 v[68:69], v[154:155], v[106:107] op_sel_hi:[1,0]
	v_pk_mul_f32 v[66:67], v[152:153], v[106:107] op_sel_hi:[1,0]
	v_pk_mul_f32 v[72:73], v[150:151], v[106:107] op_sel_hi:[1,0]
	v_pk_mul_f32 v[70:71], v[148:149], v[106:107] op_sel_hi:[1,0]
	v_pk_mul_f32 v[84:85], v[146:147], v[106:107] op_sel_hi:[1,0]
	v_pk_mul_f32 v[82:83], v[144:145], v[106:107] op_sel_hi:[1,0]
	v_pk_mul_f32 v[88:89], v[138:139], v[106:107] op_sel_hi:[1,0]
	v_pk_mul_f32 v[86:87], v[136:137], v[106:107] op_sel_hi:[1,0]
	v_pk_mul_f32 v[96:97], v[134:135], v[106:107] op_sel_hi:[1,0]
	v_pk_mul_f32 v[94:95], v[132:133], v[106:107] op_sel_hi:[1,0]
	v_pk_mul_f32 v[100:101], v[130:131], v[106:107] op_sel_hi:[1,0]
	v_pk_mul_f32 v[98:99], v[128:129], v[106:107] op_sel_hi:[1,0]
	v_pk_mul_f32 v[104:105], v[126:127], v[106:107] op_sel_hi:[1,0]
	v_pk_mul_f32 v[102:103], v[124:125], v[106:107] op_sel_hi:[1,0]
	v_pk_mul_f32 v[108:109], v[4:5], v[106:107] op_sel_hi:[1,0]
	v_pk_mul_f32 v[106:107], v[122:123], v[106:107] op_sel_hi:[1,0]
	s_setprio 1
	s_waitcnt lgkmcnt(5)
; #define LAS __attribute__((address_space(3)))
; #define MFMA16(a, b, c) __builtin_amdgcn_mfma_f32_16x16x32_bf16((a), (b), (c), 0, 0, 0)
; DI u32x2 tr4(const LAS unsigned char* p) { return __builtin_bit_cast(u32x2, __builtin_amdgcn_ds_read_tr16_b64_v4i16((LAS v4i16_t*)p)); }
; DI void at_pv(AtState& S, const f32x4 (&s1)[4], const f32x4 (&s2)[4], float alpha, float ps1, float ps2, const LAS unsigned char* buf, int hh, int fq, int tq, int tp) {
;     ...
;     for (int dh = 0; dh < 2; ++dh) {
;         bf16x8 vt[2][2];
; #pragma unroll
;         for (int d2 = 0; d2 < 2; ++d2)
; #pragma unroll
;             for (int s = 0; s < 2; ++s) { const int dt = 2 * dh + d2; const LAS unsigned char* vr = buf + AT_V + (32 * s + 4 * fq + tq) * 288 + (hh * 64 + 16 * dt + 4 * tp) * 2; vt[d2][s] = cat44(tr4(vr), tr4(vr + 16 * 288)); }
;         __builtin_amdgcn_s_setprio(1);
; #pragma unroll
;         for (int s = 0; s < 2; ++s)
; #pragma unroll
;             for (int d2 = 0; d2 < 2; ++d2) { const int dt = 2 * dh + d2; S.O1[dt] = MFMA16(vt[d2][s], p1[s], S.O1[dt]); S.O2[dt] = MFMA16(vt[d2][s], p2[s], S.O2[dt]); }
;         __builtin_amdgcn_s_setprio(0);
;         __builtin_amdgcn_sched_barrier(0);
;     }
	v_mfma_f32_16x16x32_bf16 v[66:69], v[230:233], v[214:217], v[66:69]
	v_mfma_f32_16x16x32_bf16 v[70:73], v[230:233], v[218:221], v[70:73]
	s_waitcnt lgkmcnt(2)
	v_mfma_f32_16x16x32_bf16 v[82:85], v[234:237], v[214:217], v[82:85]
	v_mfma_f32_16x16x32_bf16 v[230:233], v[234:237], v[218:221], v[86:89]
	v_mfma_f32_16x16x32_bf16 v[66:69], v[238:241], v[222:225], v[66:69]
	v_mfma_f32_16x16x32_bf16 v[86:89], v[238:241], v[226:229], v[70:73]
	s_waitcnt lgkmcnt(0)
	v_mfma_f32_16x16x32_bf16 v[70:73], v[242:245], v[222:225], v[82:85]
	v_mfma_f32_16x16x32_bf16 v[82:85], v[242:245], v[226:229], v[230:233]
	s_setprio 0
	s_nop 1
	ds_read_b64_tr_b16 v[230:231], v246 offset:17472
	ds_read_b64_tr_b16 v[234:235], v246 offset:17504
	ds_read_b64_tr_b16 v[232:233], v246 offset:22080
	ds_read_b64_tr_b16 v[236:237], v246 offset:22112
	ds_read_b64_tr_b16 v[238:239], v246 offset:26688
	ds_read_b64_tr_b16 v[240:241], v246 offset:31296
	ds_read_b64_tr_b16 v[244:245], v246 offset:31328
	ds_read_b64_tr_b16 v[242:243], v246 offset:26720
	s_setprio 1
	s_waitcnt lgkmcnt(5)
	v_mfma_f32_16x16x32_bf16 v[94:97], v[230:233], v[214:217], v[94:97]
	v_mfma_f32_16x16x32_bf16 v[98:101], v[230:233], v[218:221], v[98:101]
	s_waitcnt lgkmcnt(4)
	v_mfma_f32_16x16x32_bf16 v[102:105], v[234:237], v[214:217], v[102:105]
	v_mfma_f32_16x16x32_bf16 v[214:217], v[234:237], v[218:221], v[106:109]
	s_waitcnt lgkmcnt(2)
	v_mfma_f32_16x16x32_bf16 v[94:97], v[238:241], v[222:225], v[94:97]
	v_mfma_f32_16x16x32_bf16 v[106:109], v[238:241], v[226:229], v[98:101]
	s_waitcnt lgkmcnt(0)
	v_mfma_f32_16x16x32_bf16 v[98:101], v[242:245], v[222:225], v[102:105]
	v_mfma_f32_16x16x32_bf16 v[102:105], v[242:245], v[226:229], v[214:217]
	s_setprio 0
	s_cbranch_execnz .LBB0_1409
